# retA: hand-written lean rope/decay conversion (ILP-ordered) with the finished step's O1 = P V block folded into its VALU stream; O stores after the conversion
# baseline (speedup 1.0000x reference)
.LBB0_331:
	v_readlane_b32 s4, v254, 7
	v_readlane_b32 s5, v254, 8
	s_andn2_b64 vcc, exec, s[6:7]
	s_nop 0
	v_cndmask_b32_e64 v0, 0, 1, s[4:5]
	v_cmp_ne_u32_e64 s[78:79], 1, v0
	s_cbranch_vccnz .LBB0_407
	s_mov_b64 s[4:5], s[92:93]
	v_mov_b32_e32 v0, v172
	v_writelane_b32 v255, s78, 39
	s_and_b64 vcc, exec, s[78:79]
	v_readfirstlane_b32 s1, v0
	v_writelane_b32 v255, s79, 40
	s_cbranch_vccnz .LBB0_351
	s_add_u32 s6, s92, 0x12100000
	s_addc_u32 s7, s93, 0
	v_lshlrev_b32_e32 v1, 6, v172
	global_load_dwordx4 v[2:5], v1, s[6:7]
	global_load_dwordx4 v[6:9], v1, s[6:7] offset:16
	global_load_dwordx4 v[10:13], v1, s[6:7] offset:32
	global_load_dwordx4 v[14:17], v1, s[6:7] offset:48
	v_add_u32_e32 v1, 0x18000, v1
	s_waitcnt vmcnt(3)
	ds_write_b128 v1, v[2:5]
	s_waitcnt vmcnt(2)
	ds_write_b128 v1, v[6:9] offset:16
	s_waitcnt vmcnt(1)
	ds_write_b128 v1, v[10:13] offset:32
	s_waitcnt vmcnt(0)
	ds_write_b128 v1, v[14:17] offset:48
	s_waitcnt lgkmcnt(0)
	v_and_b32_e32 v2, 31, v172
	v_lshlrev_b32_e32 v2, 4, v2
	v_add_u32_e32 v2, 0x20000, v2
	v_mov_b32_e32 v6, 1.0
	v_mov_b32_e32 v7, 0
	v_mov_b32_e32 v8, 1.0
	v_mov_b32_e32 v9, 0
	ds_write_b128 v2, v[6:9]
	s_waitcnt lgkmcnt(0)
	s_barrier
	s_add_u32 s26, s4, 0x18e00000
	v_and_b32_e32 v2, 15, v0
	v_lshlrev_b32_e32 v6, 3, v0
	s_addc_u32 s27, s5, 0
	v_lshlrev_b32_e32 v4, 4, v2
	v_and_b32_e32 v5, 56, v6
	s_movk_i32 s6, 0x80
	s_add_u32 s23, s4, 0x2f600000
	v_and_or_b32 v128, v4, s6, v5
	v_readlane_b32 s6, v254, 43
	v_lshlrev_b32_e32 v174, 3, v5
	s_addc_u32 s95, s5, 0
	s_ashr_i32 s2, s1, 6
	v_add_u32_e32 v7, s6, v4
	v_lshl_add_u64 v[4:5], s[4:5], 0, v[174:175]
	s_mov_b64 s[4:5], 0x12100000
	s_ashr_i32 s1, s1, 7
	v_bfe_u32 v3, v0, 4, 2
	v_lshl_add_u64 v[132:133], v[4:5], 0, s[4:5]
	s_lshl_b32 s4, s2, 1
	v_lshl_or_b32 v9, s1, 4, v2
	s_movk_i32 s7, 0x210
	s_and_b32 s14, s4, 2
	v_mul_lo_u32 v4, v9, s7
	v_lshlrev_b32_e32 v12, 3, v3
	v_readlane_b32 s4, v254, 44
	v_lshlrev_b32_e32 v5, 4, v3
	v_add_u32_e32 v10, 0, v4
	v_add_u32_e32 v4, s4, v12
	s_movk_i32 s4, 0x90
	v_bfe_u32 v1, v0, 2, 2
	v_lshlrev_b32_e32 v11, 2, v3
	v_mad_u64_u32 v[134:135], s[4:5], v9, s4, v[4:5]
	v_mul_u32_u24_e32 v13, 0x210, v2
	s_lshl_b32 s4, s2, 5
	v_or_b32_e32 v1, v11, v1
	v_add3_u32 v131, 0, v13, v12
	v_and_b32_e32 v6, 24, v6
	s_add_i32 s4, s6, s4
	v_mul_u32_u24_e32 v13, 0x220, v1
	s_lshl_b32 s12, s2, 4
	v_ashrrev_i32_e32 v160, 4, v0
	s_lshl_b32 s62, s10, 3
	v_add_u32_e32 v12, s4, v6
	v_add3_u32 v135, 0, v13, v6
	s_ashr_i32 s13, s12, 31
	v_add_u32_e32 v6, 0x200, v0
	v_mul_lo_u32 v13, v160, s7
	v_ashrrev_i32_e32 v161, 4, v6
	v_add_u32_e32 v164, 0, v13
	v_and_b32_e32 v0, -16, v0
	s_cmp_ge_i32 s14, s1
	v_add_u32_e32 v13, v164, v0
	s_movk_i32 s2, 0x120
	v_mul_lo_u32 v0, v161, s7
	s_cselect_b64 s[10:11], -1, 0
	s_cmp_le_i32 s14, s1
	v_mul_lo_u32 v14, v160, s2
	v_add_u32_e32 v167, 0, v0
	v_and_b32_e32 v0, -16, v6
	v_mul_lo_u32 v15, v161, s2
	s_cselect_b64 s[4:5], -1, 0
	s_lshl_b32 s2, s14, 4
	v_add_u32_e32 v6, v167, v0
	v_or_b32_e32 v0, s2, v2
	v_writelane_b32 v255, s4, 41
	v_mul_u32_u24_e32 v16, 0x220, v0
	v_or_b32_e32 v0, s2, v11
	v_writelane_b32 v255, s5, 42
	v_cmp_le_i32_e64 s[4:5], v0, v9
	v_or_b32_e32 v17, 1, v0
	v_cmp_lt_i32_e64 s[8:9], v0, v9
	v_writelane_b32 v255, s4, 43
	v_cmp_ge_i32_e64 s[6:7], v0, v9
	s_lshl_b32 s63, s14, 5
	v_writelane_b32 v255, s5, 44
	v_cmp_ge_i32_e64 s[4:5], v17, v9
	v_writelane_b32 v255, s8, 45
	v_or_b32_e32 v17, 2, v0
	v_or_b32_e32 v0, 3, v0
	v_writelane_b32 v255, s9, 46
	v_cmp_le_i32_e64 s[8:9], v17, v9
	s_or_b32 s2, s14, 1
	s_cmp_ge_i32 s2, s1
	v_writelane_b32 v255, s8, 47
	v_cmp_ge_i32_e64 s[98:99], v0, v9
	v_cmp_ge_i32_e64 s[56:57], v17, v9
	v_writelane_b32 v255, s9, 48
	v_cmp_le_i32_e64 s[8:9], v0, v9
	v_lshlrev_b32_e32 v129, 1, v128
	v_add_u32_e32 v8, 0, v5
	v_writelane_b32 v255, s8, 49
	v_mul_u32_u24_e32 v1, 0x120, v1
	v_lshlrev_b32_e32 v130, 3, v2
	v_writelane_b32 v255, s9, 50
	s_cselect_b64 s[8:9], -1, 0
	s_cmp_lt_i32 s14, s1
	s_cselect_b64 s[72:73], -1, 0
	s_lshl_b32 s1, s2, 4
	v_or_b32_e32 v0, s1, v2
	v_mul_u32_u24_e32 v17, 0x220, v0
	v_or_b32_e32 v0, s1, v11
	v_cmp_le_i32_e64 s[14:15], v0, v9
	v_or_b32_e32 v11, 1, v0
	v_cmp_ge_i32_e64 s[86:87], v11, v9
	v_writelane_b32 v255, s14, 51
	v_or_b32_e32 v11, 2, v0
	v_cmp_ge_i32_e64 s[96:97], v0, v9
	v_writelane_b32 v255, s15, 52
	v_cmp_lt_i32_e64 s[14:15], v0, v9
	v_or_b32_e32 v0, 3, v0
	v_cmp_ge_i32_e64 s[82:83], v11, v9
	v_writelane_b32 v255, s14, 53
	v_cmp_ge_i32_e64 s[80:81], v0, v9
	v_cmp_gt_u32_e64 s[38:39], 8, v2
	v_writelane_b32 v255, s15, 54
	v_cmp_le_i32_e64 s[14:15], v11, v9
	v_sub_u32_e32 v162, 64, v160
	v_add_u32_e32 v163, 1, v160
	v_writelane_b32 v255, s14, 55
	v_sub_u32_e32 v165, 64, v161
	v_add_u32_e32 v166, 1, v161
	v_writelane_b32 v255, s15, 56
	v_cmp_le_i32_e64 s[14:15], v0, v9
	v_mul_u32_u24_e32 v9, 0x90, v2
	v_lshlrev_b32_e32 v0, 14, v3
	v_writelane_b32 v255, s14, 57
	s_lshl_b32 s22, s2, 5
	s_lshl_b64 s[30:31], s[12:13], 1
	v_writelane_b32 v255, s15, 58
	v_lshlrev_b32_e32 v136, 13, v2
	v_lshrrev_b32_e32 v138, 11, v0
	v_add_u32_e32 v168, v13, v129
	v_add_u32_e32 v169, v7, v14
	v_add_u32_e32 v170, v6, v129
	v_add_u32_e32 v171, v7, v15
	v_add_u32_e32 v177, v8, v16
	v_add_u32_e32 v184, v8, v17
	v_add_u32_e32 v185, v12, v1
	v_add_u32_e32 v186, v4, v9
	v_add_u32_e32 v187, v10, v5
	v_readlane_b32 s2, v255, 15
	s_branch .LBB0_335

.LBB0_339:
	s_lshr_b32 s14, s2, 2
	s_and_b32 s1, s2, 6
	s_and_b32 s14, s14, 8
	s_or_b32 s16, s14, s1
	s_lshr_b32 s14, s16, 1
	s_or_b32 s90, s14, s62
	s_ashr_i32 s1, s2, 6
	s_lshl_b64 s[66:67], s[90:91], 2
	s_add_u32 s12, s12, s66
	s_addc_u32 s13, s13, s67
	global_load_dword v22, v175, s[12:13]
	s_lshl_b32 s33, s1, 8
	s_addk_i32 s33, 0x2000
	s_mov_b32 s15, 0x3fb8aa3b
	s_or_b32 s40, s40, s33
	v_mov_b64_e32 v[2:3], s[26:27]
	s_waitcnt vmcnt(26)
	v_add_u32_e32 v4, s40, v160
	s_mov_b32 s13, s91
	s_lshl_b32 s12, s16, 8
	v_mad_i64_i32 v[4:5], vcc, v4, s3, v[2:3]
	v_lshlrev_b32_e32 v174, 1, v128
	v_lshl_add_u64 v[6:7], v[4:5], 0, s[12:13]
	s_waitcnt vmcnt(24)
	v_lshl_add_u64 v[12:13], v[6:7], 0, v[174:175]
	s_mov_b32 s43, 0xc2ce8ed0
	s_mov_b32 s44, 0x42b17218
	s_lshl_b32 s42, s2, 4
	s_and_b32 s67, s42, 0x180
	s_mov_b32 s42, 0x3f2aaaab
	s_lshl_b32 s90, s16, 9
	s_mov_b32 s17, s91
	s_lshl_b32 s41, s16, 7
	s_lshl_b32 s16, s67, 1
	v_lshl_add_u64 v[4:5], v[4:5], 0, s[90:91]
	v_lshlrev_b32_e32 v140, 1, v130
	v_mov_b32_e32 v141, v175
	s_waitcnt vmcnt(22)
	v_lshl_add_u64 v[20:21], v[4:5], 0, s[16:17]
	v_lshl_add_u64 v[20:21], v[20:21], 0, v[140:141]
	global_load_dwordx4 v[4:7], v[12:13], off
	global_load_dwordx4 v[8:11], v[12:13], off offset:128
	v_cvt_f32_i32_e32 v44, v44
	v_cvt_f32_i32_e32 v1, v1
	s_lshl_b32 s1, s1, 11
	v_mov_b32_e32 v137, v175
	v_mov_b32_e32 v0, 0
	v_mov_b32_e32 v139, v175
	s_mulk_i32 s19, 0x2400
	v_mov_b32_e32 v52, v0
	v_mov_b32_e32 v53, v0
	v_mov_b32_e32 v54, v0
	v_mov_b32_e32 v55, v0
	v_mov_b32_e32 v56, v0
	v_mov_b32_e32 v57, v0
	v_mov_b32_e32 v58, v0
	v_mov_b32_e32 v59, v0
	v_mov_b32_e32 v60, v0
	v_mov_b32_e32 v61, v0
	v_mov_b32_e32 v62, v0
	v_mov_b32_e32 v63, v0
	v_mov_b32_e32 v64, v0
	v_mov_b32_e32 v65, v0
	v_mov_b32_e32 v66, v0
	v_mov_b32_e32 v67, v0
	v_mov_b32_e32 v68, v0
	v_mov_b32_e32 v69, v0
	v_mov_b32_e32 v70, v0
	v_mov_b32_e32 v71, v0
	v_mov_b32_e32 v72, v0
	v_mov_b32_e32 v73, v0
	v_mov_b32_e32 v74, v0
	v_mov_b32_e32 v75, v0
	v_mov_b32_e32 v76, v0
	v_mov_b32_e32 v77, v0
	v_mov_b32_e32 v78, v0
	v_mov_b32_e32 v79, v0
	v_mov_b32_e32 v80, v0
	v_mov_b32_e32 v81, v0
	v_mov_b32_e32 v82, v0
	v_mov_b32_e32 v83, v0
	v_mov_b32_e32 v84, v0
	v_mov_b32_e32 v85, v0
	v_mov_b32_e32 v86, v0
	v_mov_b32_e32 v87, v0
	v_mov_b32_e32 v88, v0
	v_mov_b32_e32 v89, v0
	v_mov_b32_e32 v90, v0
	v_mov_b32_e32 v91, v0
	v_mov_b32_e32 v100, v0
	v_mov_b32_e32 v101, v0
	v_mov_b32_e32 v102, v0
	v_mov_b32_e32 v103, v0
	s_waitcnt vmcnt(2)
	v_mul_f32_e32 v14, 0x3fb8aa3b, v22
	v_fma_f32 v15, v22, s15, -v14
	v_rndne_f32_e32 v16, v14
	v_fmac_f32_e32 v15, 0x32a5705f, v22
	v_sub_f32_e32 v14, v14, v16
	v_add_f32_e32 v14, v14, v15
	v_cvt_i32_f32_e32 v23, v16
	v_exp_f32_e32 v24, v14
	v_add_co_u32_e32 v16, vcc, s21, v12
	v_mov_b32_e32 v92, v0
	s_nop 0
	v_addc_co_u32_e32 v17, vcc, 0, v13, vcc
	v_ldexp_f32 v23, v24, v23
	v_cmp_ngt_f32_e32 vcc, s43, v22
	global_load_dwordx4 v[12:15], v[16:17], off
	s_nop 0
	global_load_dwordx4 v[16:19], v[16:17], off offset:128
	v_cndmask_b32_e32 v23, 0, v23, vcc
	v_cmp_nlt_f32_e32 vcc, s44, v22
	v_mov_b32_e32 v93, v0
	v_mov_b32_e32 v94, v0
	v_cndmask_b32_e32 v22, v252, v23, vcc
	v_add_f32_e32 v23, 1.0, v22
	v_add_f32_e32 v26, -1.0, v23
	v_frexp_mant_f32_e32 v27, v23
	v_cvt_f64_f32_e32 v[24:25], v23
	v_sub_f32_e32 v28, v26, v23
	v_frexp_exp_i32_f64_e32 v24, v[24:25]
	v_cmp_gt_f32_e32 vcc, s42, v27
	v_sub_f32_e32 v26, v22, v26
	v_add_f32_e32 v25, 1.0, v28
	v_subbrev_co_u32_e32 v24, vcc, 0, v24, vcc
	v_add_f32_e32 v25, v26, v25
	v_sub_u32_e32 v26, 0, v24
	v_ldexp_f32 v23, v23, v26
	v_ldexp_f32 v25, v25, v26
	v_add_f32_e32 v26, -1.0, v23
	v_add_f32_e32 v28, 1.0, v23
	v_add_f32_e32 v27, 1.0, v26
	v_add_f32_e32 v29, -1.0, v28
	v_sub_f32_e32 v27, v23, v27
	v_sub_f32_e32 v23, v23, v29
	v_add_f32_e32 v23, v25, v23
	v_add_f32_e32 v29, v25, v27
	v_add_f32_e32 v25, v28, v23
	v_rcp_f32_e32 v32, v25
	v_add_f32_e32 v27, v26, v29
	v_sub_f32_e32 v28, v28, v25
	v_add_f32_e32 v23, v23, v28
	v_mul_f32_e32 v34, v27, v32
	v_mul_f32_e32 v28, v25, v34
	v_fma_f32 v30, v34, v25, -v28
	v_sub_f32_e32 v26, v26, v27
	v_fmac_f32_e32 v30, v34, v23
	v_add_f32_e32 v33, v29, v26
	v_add_f32_e32 v26, v28, v30
	v_sub_f32_e32 v29, v27, v26
	v_mov_b32_e32 v31, v26
	v_pk_add_f32 v[26:27], v[26:27], v[28:29] neg_lo:[0,1] neg_hi:[0,1]
	v_cvt_f32_i32_e32 v24, v24
	v_pk_add_f32 v[26:27], v[26:27], v[30:31] neg_lo:[0,1] neg_hi:[0,1]
	s_mov_b32 s42, 0x3f317218
	v_add_f32_e32 v27, v33, v27
	v_add_f32_e32 v26, v26, v27
	v_add_f32_e32 v27, v29, v26
	v_mul_f32_e32 v31, v32, v27
	v_mul_f32_e32 v28, v25, v31
	v_fma_f32 v30, v31, v25, -v28
	v_sub_f32_e32 v29, v29, v27
	v_fmac_f32_e32 v30, v31, v23
	v_add_f32_e32 v33, v26, v29
	v_add_f32_e32 v35, v34, v31
	v_add_f32_e32 v26, v28, v30
	v_sub_f32_e32 v25, v35, v34
	v_sub_f32_e32 v29, v27, v26
	v_sub_f32_e32 v23, v31, v25
	v_mov_b32_e32 v31, v26
	v_pk_add_f32 v[26:27], v[26:27], v[28:29] neg_lo:[0,1] neg_hi:[0,1]
	v_mov_b32_e32 v95, v0
	v_pk_add_f32 v[26:27], v[26:27], v[30:31] neg_lo:[0,1] neg_hi:[0,1]
	v_mov_b32_e32 v96, v0
	v_add_f32_e32 v25, v33, v27
	v_add_f32_e32 v25, v26, v25
	v_add_f32_e32 v25, v29, v25
	v_mul_f32_e32 v25, v32, v25
	v_add_f32_e32 v23, v23, v25
	v_add_f32_e32 v25, v35, v23
	v_mul_f32_e32 v26, v25, v25
	v_mov_b32_e32 v29, 0x3ecc95a3
	v_fmamk_f32 v29, v26, 0x3e9b6dac, v29
	v_sub_f32_e32 v28, v25, v35
	v_ldexp_f32 v27, v25, 1
	v_mul_f32_e32 v25, v25, v26
	v_fmaak_f32 v179, v26, v29, 0x3f2aaada
	v_sub_f32_e32 v23, v23, v28
	v_pk_mul_f32 v[28:29], v[24:25], v[178:179]
	v_ldexp_f32 v23, v23, 1
	v_fma_f32 v26, v24, s42, -v28
	v_fmac_f32_e32 v26, 0xb102e308, v24
	v_pk_add_f32 v[24:25], v[28:29], v[26:27]
	v_mov_b32_e32 v30, v28
	v_sub_f32_e32 v31, v25, v27
	v_pk_add_f32 v[32:33], v[24:25], v[28:29] neg_lo:[0,1] neg_hi:[0,1]
	v_sub_f32_e32 v29, v29, v31
	v_add_f32_e32 v31, v23, v29
	v_pk_add_f32 v[36:37], v[24:25], v[30:31]
	v_mov_b32_e32 v27, v24
	v_mov_b32_e32 v33, v37
	v_pk_add_f32 v[38:39], v[26:27], v[32:33] neg_lo:[0,1] neg_hi:[0,1]
	v_pk_add_f32 v[26:27], v[26:27], v[32:33]
	v_mov_b32_e32 v28, v25
	v_mov_b32_e32 v35, v24
	v_pk_add_f32 v[24:25], v[26:27], v[24:25] op_sel:[1,0] op_sel_hi:[0,1] neg_lo:[0,1] neg_hi:[0,1]
	v_mov_b32_e32 v34, v31
	v_mov_b32_e32 v30, v37
	v_mov_b32_e32 v31, v27
	v_mov_b32_e32 v29, v24
	v_pk_add_f32 v[32:33], v[36:37], v[24:25] op_sel_hi:[1,0] neg_lo:[0,1] neg_hi:[0,1]
	v_pk_add_f32 v[24:25], v[30:31], v[28:29] neg_lo:[0,1] neg_hi:[0,1]
	v_mov_b32_e32 v32, v38
	v_pk_add_f32 v[24:25], v[34:35], v[24:25] neg_lo:[0,1] neg_hi:[0,1]
	v_mov_b32_e32 v39, v27
	v_pk_add_f32 v[28:29], v[32:33], v[24:25]
	s_mov_b32 s42, 0x7f800000
	v_pk_add_f32 v[30:31], v[28:29], v[28:29] op_sel:[0,1] op_sel_hi:[1,0]
	v_cmp_neq_f32_e32 vcc, s42, v22
	v_pk_add_f32 v[26:27], v[26:27], v[30:31] op_sel:[1,0] op_sel_hi:[0,1]
	v_mov_b32_e32 v29, v26
	v_mov_b32_e32 v25, v30
	v_pk_add_f32 v[30:31], v[28:29], v[38:39] neg_lo:[0,1] neg_hi:[0,1]
	s_mov_b32 s42, 0x33800000
	v_sub_f32_e32 v23, v28, v30
	v_pk_add_f32 v[24:25], v[24:25], v[30:31] neg_lo:[0,1] neg_hi:[0,1]
	v_sub_f32_e32 v23, v38, v23
	v_add_f32_e32 v23, v24, v23
	v_add_f32_e32 v23, v23, v25
	v_add_f32_e32 v23, v26, v23
	v_cndmask_b32_e32 v23, v252, v23, vcc
	v_cmp_lt_f32_e64 vcc, |v22|, s42
	v_mov_b32_e32 v97, v0
	v_mov_b32_e32 v98, v0
	v_cndmask_b32_e32 v45, v23, v22, vcc
	v_add_co_u32_e32 v20, vcc, s18, v20
	v_add_u32_e32 v22, s40, v161
	s_nop 0
	v_addc_co_u32_e32 v21, vcc, 0, v21, vcc
	v_mad_i64_i32 v[2:3], vcc, v22, s3, v[2:3]
	v_mul_f32_e32 v46, 0xc2800000, v45
	v_lshl_add_u64 v[22:23], v[2:3], 0, s[12:13]
	v_lshl_add_u64 v[28:29], v[22:23], 0, v[174:175]
	v_lshl_add_u64 v[2:3], v[2:3], 0, s[90:91]
	v_mul_f32_e32 v38, 0x3fb8aa3b, v46
	v_add_co_u32_e32 v36, vcc, s21, v28
	v_lshl_add_u64 v[2:3], v[2:3], 0, s[16:17]
	v_fma_f32 v39, v46, s15, -v38
	v_rndne_f32_e32 v40, v38
	v_addc_co_u32_e32 v37, vcc, 0, v29, vcc
	v_lshl_add_u64 v[2:3], v[2:3], 0, v[140:141]
	v_fmac_f32_e32 v39, 0x32a5705f, v46
	v_sub_f32_e32 v38, v38, v40
	v_add_f32_e32 v38, v38, v39
	v_add_co_u32_e32 v2, vcc, s18, v2
	global_load_dwordx4 v[20:23], v[20:21], off
	s_nop 0
	global_load_dwordx4 v[24:27], v[28:29], off
	s_nop 0
	global_load_dwordx4 v[28:31], v[28:29], off offset:128
	s_nop 0
	global_load_dwordx4 v[32:35], v[36:37], off
	v_exp_f32_e32 v47, v38
	v_cvt_i32_f32_e32 v48, v40
	v_addc_co_u32_e32 v3, vcc, 0, v3, vcc
	global_load_dwordx4 v[36:39], v[36:37], off offset:128
	s_nop 0
	global_load_dwordx4 v[40:43], v[2:3], off
	v_ldexp_f32 v2, v47, v48
	v_cmp_ngt_f32_e32 vcc, s43, v46
	s_add_u32 s13, s23, s90
	s_addc_u32 s14, s95, 0
	v_cndmask_b32_e32 v2, 0, v2, vcc
	v_cmp_nlt_f32_e32 vcc, s44, v46
	v_mul_f32_e32 v46, v45, v44
	v_mul_f32_e64 v44, v44, -v45
	v_cndmask_b32_e32 v142, v252, v2, vcc
	v_mul_f32_e32 v2, 0x3fb8aa3b, v46
	v_fma_f32 v3, v46, s15, -v2
	v_rndne_f32_e32 v47, v2
	v_fmac_f32_e32 v3, 0x32a5705f, v46
	v_sub_f32_e32 v2, v2, v47
	v_add_f32_e32 v2, v2, v3
	v_exp_f32_e32 v48, v2
	v_cvt_i32_f32_e32 v47, v47
	v_cmp_ngt_f32_e32 vcc, s43, v46
	s_add_u32 s13, s13, s16
	s_addc_u32 s14, s14, 0
	v_ldexp_f32 v47, v48, v47
	v_mul_f32_e32 v48, 0x3fb8aa3b, v44
	v_fma_f32 v49, v44, s15, -v48
	v_rndne_f32_e32 v50, v48
	v_fmac_f32_e32 v49, 0x32a5705f, v44
	v_sub_f32_e32 v48, v48, v50
	v_add_f32_e32 v48, v48, v49
	v_exp_f32_e32 v48, v48
	v_cvt_i32_f32_e32 v49, v50
	v_cndmask_b32_e32 v47, 0, v47, vcc
	v_cmp_nlt_f32_e32 vcc, s44, v46
	s_add_u32 s16, s13, s30
	s_addc_u32 s17, s14, s31
	v_cndmask_b32_e32 v46, v252, v47, vcc
	v_ldexp_f32 v47, v48, v49
	v_mul_f32_e32 v48, v45, v1
	v_mul_f32_e32 v49, 0x3fb8aa3b, v48
	v_cmp_ngt_f32_e32 vcc, s43, v44
	v_fma_f32 v50, v48, s15, -v49
	v_rndne_f32_e32 v51, v49
	v_mul_f32_e64 v1, v1, -v45
	v_cndmask_b32_e32 v47, 0, v47, vcc
	v_fmac_f32_e32 v50, 0x32a5705f, v48
	v_sub_f32_e32 v49, v49, v51
	v_cmp_nlt_f32_e32 vcc, s44, v44
	v_mul_f32_e32 v45, 0x3fb8aa3b, v1
	v_lshl_add_u64 v[2:3], s[16:17], 0, v[136:137]
	v_add_f32_e32 v49, v49, v50
	v_cndmask_b32_e32 v137, v252, v47, vcc
	v_mul_f32_e32 v179, 0x3d800000, v46
	v_fma_f32 v46, v1, s15, -v45
	v_rndne_f32_e32 v47, v45
	v_exp_f32_e32 v49, v49
	v_cvt_i32_f32_e32 v50, v51
	v_fmac_f32_e32 v46, 0x32a5705f, v1
	v_sub_f32_e32 v45, v45, v47
	v_add_f32_e32 v45, v45, v46
	v_exp_f32_e32 v45, v45
	v_cvt_i32_f32_e32 v46, v47
	v_ldexp_f32 v44, v49, v50
	v_cmp_ngt_f32_e32 vcc, s43, v48
	v_mov_b32_e32 v144, v142
	v_ldexp_f32 v45, v45, v46
	v_cndmask_b32_e32 v44, 0, v44, vcc
	v_cmp_nlt_f32_e32 vcc, s44, v48
	v_mov_b32_e32 v145, v142
	v_lshl_add_u64 v[146:147], v[2:3], 0, v[138:139]
	v_cndmask_b32_e32 v44, v252, v44, vcc
	v_cmp_ngt_f32_e32 vcc, s43, v1
	v_mul_f32_e32 v189, 0x3d800000, v44
	s_mov_b32 s40, -4
	v_cndmask_b32_e32 v45, 0, v45, vcc
	v_cmp_nlt_f32_e32 vcc, s44, v1
	s_lshl_b32 s90, s41, 1
	s_lshl_b32 s66, s12, 1
	v_cndmask_b32_e32 v188, v252, v45, vcc
	s_lshl_b32 s14, s67, 1
	v_mov_b32_e32 v1, v0
	v_mov_b32_e32 v2, v0
	v_mov_b32_e32 v3, v0
	v_mov_b32_e32 v44, v0
	v_mov_b32_e32 v45, v0
	v_mov_b32_e32 v46, v0
	v_mov_b32_e32 v47, v0
	v_mov_b32_e32 v48, v0
	v_mov_b32_e32 v49, v0
	v_mov_b32_e32 v50, v0
	v_mov_b32_e32 v51, v0
	v_mov_b32_e32 v99, v0
	s_waitcnt vmcnt(0)
	v_add_co_u32_e64 v104, s[16:17], s40, 4
	s_nop 0
	v_readfirstlane_b32 s13, v104
	s_and_b64 vcc, s[16:17], exec
	s_cselect_b32 s41, s13, s40
	s_cselect_b32 s42, 3, 31
	s_sub_i32 s67, s42, s41
	s_and_b64 s[42:43], exec, s[74:75]
	s_cselect_b32 s41, s41, s67
	s_and_b64 vcc, s[16:17], exec
	s_cselect_b64 s[44:45], -1, s[38:39]
	s_cselect_b32 s46, 64, s41
	v_mov_b32_e32 v242, s46
	v_cndmask_b32_e64 v242, v160, v242, s[44:45]
	v_and_b32_e32 v226, 0xff, v174
	v_lshlrev_b32_e32 v226, 2, v226
	v_lshl_add_u32 v242, v242, 9, v226
	v_add_u32_e32 v242, 0x18000, v242
	ds_read_b128 v[194:197], v242
	ds_read_b128 v[198:201], v242 offset:16
	ds_read_b128 v[202:205], v242 offset:32
	ds_read_b128 v[206:209], v242 offset:48
	s_waitcnt vmcnt(0)
	v_lshlrev_b32_e32 v226, 16, v4
	v_and_b32_e32 v227, 0xffff0000, v4
	v_lshlrev_b32_e32 v228, 16, v8
	v_and_b32_e32 v229, 0xffff0000, v8
	v_lshlrev_b32_e32 v230, 16, v12
	v_and_b32_e32 v231, 0xffff0000, v12
	v_lshlrev_b32_e32 v232, 16, v16
	v_and_b32_e32 v233, 0xffff0000, v16
	s_waitcnt lgkmcnt(3)
	v_mul_f32_e32 v234, v228, v195
	v_mul_f32_e32 v235, v232, v195
	v_mul_f32_e32 v236, v229, v197
	v_mul_f32_e32 v237, v233, v197
	v_mul_f32_e32 v238, v228, v194
	v_mul_f32_e32 v239, v232, v194
	v_mul_f32_e32 v240, v229, v196
	v_mul_f32_e32 v241, v233, v196
	v_fma_f32 v228, v226, v195, v238
	v_fma_f32 v232, v230, v195, v239
	v_fma_f32 v229, v227, v197, v240
	v_fma_f32 v233, v231, v197, v241
	v_fma_f32 v226, v226, v194, -v234
	v_fma_f32 v230, v230, v194, -v235
	v_fma_f32 v227, v227, v196, -v236
	v_fma_f32 v231, v231, v196, -v237
	v_mul_f32_e32 v228, v137, v228
	v_mul_f32_e32 v229, v137, v229
	v_mul_f32_e32 v232, v179, v232
	v_mul_f32_e32 v233, v179, v233
	v_mul_f32_e32 v226, v137, v226
	v_mul_f32_e32 v227, v137, v227
	v_mul_f32_e32 v230, v179, v230
	v_mul_f32_e32 v231, v179, v231
	v_cvt_pk_bf16_f32 v8, v228, v229
	v_cvt_pk_bf16_f32 v16, v232, v233
	v_cvt_pk_bf16_f32 v4, v226, v227
	v_cvt_pk_bf16_f32 v12, v230, v231
	v_lshlrev_b32_e32 v226, 16, v5
	v_and_b32_e32 v227, 0xffff0000, v5
	v_lshlrev_b32_e32 v228, 16, v9
	v_and_b32_e32 v229, 0xffff0000, v9
	v_lshlrev_b32_e32 v230, 16, v13
	v_and_b32_e32 v231, 0xffff0000, v13
	v_lshlrev_b32_e32 v232, 16, v17
	v_and_b32_e32 v233, 0xffff0000, v17
	s_waitcnt lgkmcnt(2)
	v_mul_f32_e32 v234, v228, v199
	v_mul_f32_e32 v235, v232, v199
	v_mul_f32_e32 v236, v229, v201
	v_mul_f32_e32 v237, v233, v201
	v_mul_f32_e32 v238, v228, v198
	v_mul_f32_e32 v239, v232, v198
	v_mul_f32_e32 v240, v229, v200
	v_mul_f32_e32 v241, v233, v200
	v_fma_f32 v228, v226, v199, v238
	v_fma_f32 v232, v230, v199, v239
	v_fma_f32 v229, v227, v201, v240
	v_fma_f32 v233, v231, v201, v241
	v_fma_f32 v226, v226, v198, -v234
	v_fma_f32 v230, v230, v198, -v235
	v_fma_f32 v227, v227, v200, -v236
	v_fma_f32 v231, v231, v200, -v237
	v_mul_f32_e32 v228, v137, v228
	v_mul_f32_e32 v229, v137, v229
	v_mul_f32_e32 v232, v179, v232
	v_mul_f32_e32 v233, v179, v233
	v_mul_f32_e32 v226, v137, v226
	v_mul_f32_e32 v227, v137, v227
	v_mul_f32_e32 v230, v179, v230
	v_mul_f32_e32 v231, v179, v231
	v_cvt_pk_bf16_f32 v9, v228, v229
	v_cvt_pk_bf16_f32 v17, v232, v233
	v_cvt_pk_bf16_f32 v5, v226, v227
	v_cvt_pk_bf16_f32 v13, v230, v231
	v_lshlrev_b32_e32 v226, 16, v6
	v_and_b32_e32 v227, 0xffff0000, v6
	v_lshlrev_b32_e32 v228, 16, v10
	v_and_b32_e32 v229, 0xffff0000, v10
	v_lshlrev_b32_e32 v230, 16, v14
	v_and_b32_e32 v231, 0xffff0000, v14
	v_lshlrev_b32_e32 v232, 16, v18
	v_and_b32_e32 v233, 0xffff0000, v18
	s_waitcnt lgkmcnt(1)
	v_mul_f32_e32 v234, v228, v203
	v_mul_f32_e32 v235, v232, v203
	v_mul_f32_e32 v236, v229, v205
	v_mul_f32_e32 v237, v233, v205
	v_mul_f32_e32 v238, v228, v202
	v_mul_f32_e32 v239, v232, v202
	v_mul_f32_e32 v240, v229, v204
	v_mul_f32_e32 v241, v233, v204
	v_fma_f32 v228, v226, v203, v238
	v_fma_f32 v232, v230, v203, v239
	v_fma_f32 v229, v227, v205, v240
	v_fma_f32 v233, v231, v205, v241
	v_fma_f32 v226, v226, v202, -v234
	v_fma_f32 v230, v230, v202, -v235
	v_fma_f32 v227, v227, v204, -v236
	v_fma_f32 v231, v231, v204, -v237
	v_mul_f32_e32 v228, v137, v228
	v_mul_f32_e32 v229, v137, v229
	v_mul_f32_e32 v232, v179, v232
	v_mul_f32_e32 v233, v179, v233
	v_mul_f32_e32 v226, v137, v226
	v_mul_f32_e32 v227, v137, v227
	v_mul_f32_e32 v230, v179, v230
	v_mul_f32_e32 v231, v179, v231
	v_cvt_pk_bf16_f32 v10, v228, v229
	v_cvt_pk_bf16_f32 v18, v232, v233
	v_cvt_pk_bf16_f32 v6, v226, v227
	v_cvt_pk_bf16_f32 v14, v230, v231
	v_mov_b32_e32 v243, s46
	v_cndmask_b32_e64 v243, v161, v243, s[44:45]
	v_and_b32_e32 v226, 0xff, v174
	v_lshlrev_b32_e32 v226, 2, v226
	v_lshl_add_u32 v243, v243, 9, v226
	v_add_u32_e32 v243, 0x18000, v243
	ds_read_b128 v[210:213], v243
	ds_read_b128 v[214:217], v243 offset:16
	ds_read_b128 v[218:221], v243 offset:32
	ds_read_b128 v[222:225], v243 offset:48
	v_lshlrev_b32_e32 v226, 16, v7
	v_and_b32_e32 v227, 0xffff0000, v7
	v_lshlrev_b32_e32 v228, 16, v11
	v_and_b32_e32 v229, 0xffff0000, v11
	v_lshlrev_b32_e32 v230, 16, v15
	v_and_b32_e32 v231, 0xffff0000, v15
	v_lshlrev_b32_e32 v232, 16, v19
	v_and_b32_e32 v233, 0xffff0000, v19
	s_waitcnt lgkmcnt(4)
	v_mul_f32_e32 v234, v228, v207
	v_mul_f32_e32 v235, v232, v207
	v_mul_f32_e32 v236, v229, v209
	v_mul_f32_e32 v237, v233, v209
	v_mul_f32_e32 v238, v228, v206
	v_mul_f32_e32 v239, v232, v206
	v_mul_f32_e32 v240, v229, v208
	v_mul_f32_e32 v241, v233, v208
	v_fma_f32 v228, v226, v207, v238
	v_fma_f32 v232, v230, v207, v239
	v_fma_f32 v229, v227, v209, v240
	v_fma_f32 v233, v231, v209, v241
	v_fma_f32 v226, v226, v206, -v234
	v_fma_f32 v230, v230, v206, -v235
	v_fma_f32 v227, v227, v208, -v236
	v_fma_f32 v231, v231, v208, -v237
	v_mul_f32_e32 v228, v137, v228
	v_mul_f32_e32 v229, v137, v229
	v_mul_f32_e32 v232, v179, v232
	v_mul_f32_e32 v233, v179, v233
	v_mul_f32_e32 v226, v137, v226
	v_mul_f32_e32 v227, v137, v227
	v_mul_f32_e32 v230, v179, v230
	v_mul_f32_e32 v231, v179, v231
	v_cvt_pk_bf16_f32 v11, v228, v229
	v_cvt_pk_bf16_f32 v19, v232, v233
	v_cvt_pk_bf16_f32 v7, v226, v227
	v_cvt_pk_bf16_f32 v15, v230, v231
	v_add_u32_e32 v248, v164, v129
	ds_write_b128 v248, v[4:7]
	ds_write_b128 v248, v[8:11] offset:128
	ds_write_b128 v168, v[12:15] offset:33792
	ds_write_b128 v168, v[16:19] offset:33920
	s_waitcnt vmcnt(0)
	ds_write_b128 v169, v[20:23]
	s_waitcnt vmcnt(0)
	v_lshlrev_b32_e32 v226, 16, v24
	v_and_b32_e32 v227, 0xffff0000, v24
	v_lshlrev_b32_e32 v228, 16, v28
	v_and_b32_e32 v229, 0xffff0000, v28
	v_lshlrev_b32_e32 v230, 16, v32
	v_and_b32_e32 v231, 0xffff0000, v32
	v_lshlrev_b32_e32 v232, 16, v36
	v_and_b32_e32 v233, 0xffff0000, v36
	s_waitcnt lgkmcnt(8)
	v_mul_f32_e32 v234, v228, v211
	v_mul_f32_e32 v235, v232, v211
	v_mul_f32_e32 v236, v229, v213
	v_mul_f32_e32 v237, v233, v213
	v_mul_f32_e32 v238, v228, v210
	v_mul_f32_e32 v239, v232, v210
	v_mul_f32_e32 v240, v229, v212
	v_mul_f32_e32 v241, v233, v212
	v_fma_f32 v228, v226, v211, v238
	v_fma_f32 v232, v230, v211, v239
	v_fma_f32 v229, v227, v213, v240
	v_fma_f32 v233, v231, v213, v241
	v_fma_f32 v226, v226, v210, -v234
	v_fma_f32 v230, v230, v210, -v235
	v_fma_f32 v227, v227, v212, -v236
	v_fma_f32 v231, v231, v212, -v237
	v_mul_f32_e32 v228, v188, v228
	v_mul_f32_e32 v229, v188, v229
	v_mul_f32_e32 v232, v189, v232
	v_mul_f32_e32 v233, v189, v233
	v_mul_f32_e32 v226, v188, v226
	v_mul_f32_e32 v227, v188, v227
	v_mul_f32_e32 v230, v189, v230
	v_mul_f32_e32 v231, v189, v231
	v_cvt_pk_bf16_f32 v28, v228, v229
	v_cvt_pk_bf16_f32 v36, v232, v233
	v_cvt_pk_bf16_f32 v24, v226, v227
	v_cvt_pk_bf16_f32 v32, v230, v231
	v_lshlrev_b32_e32 v226, 16, v25
	v_and_b32_e32 v227, 0xffff0000, v25
	v_lshlrev_b32_e32 v228, 16, v29
	v_and_b32_e32 v229, 0xffff0000, v29
	v_lshlrev_b32_e32 v230, 16, v33
	v_and_b32_e32 v231, 0xffff0000, v33
	v_lshlrev_b32_e32 v232, 16, v37
	v_and_b32_e32 v233, 0xffff0000, v37
	s_waitcnt lgkmcnt(7)
	v_mul_f32_e32 v234, v228, v215
	v_mul_f32_e32 v235, v232, v215
	v_mul_f32_e32 v236, v229, v217
	v_mul_f32_e32 v237, v233, v217
	v_mul_f32_e32 v238, v228, v214
	v_mul_f32_e32 v239, v232, v214
	v_mul_f32_e32 v240, v229, v216
	v_mul_f32_e32 v241, v233, v216
	v_fma_f32 v228, v226, v215, v238
	v_fma_f32 v232, v230, v215, v239
	v_fma_f32 v229, v227, v217, v240
	v_fma_f32 v233, v231, v217, v241
	v_fma_f32 v226, v226, v214, -v234
	v_fma_f32 v230, v230, v214, -v235
	v_fma_f32 v227, v227, v216, -v236
	v_fma_f32 v231, v231, v216, -v237
	v_mul_f32_e32 v228, v188, v228
	v_mul_f32_e32 v229, v188, v229
	v_mul_f32_e32 v232, v189, v232
	v_mul_f32_e32 v233, v189, v233
	v_mul_f32_e32 v226, v188, v226
	v_mul_f32_e32 v227, v188, v227
	v_mul_f32_e32 v230, v189, v230
	v_mul_f32_e32 v231, v189, v231
	v_cvt_pk_bf16_f32 v29, v228, v229
	v_cvt_pk_bf16_f32 v37, v232, v233
	v_cvt_pk_bf16_f32 v25, v226, v227
	v_cvt_pk_bf16_f32 v33, v230, v231
	v_lshlrev_b32_e32 v226, 16, v26
	v_and_b32_e32 v227, 0xffff0000, v26
	v_lshlrev_b32_e32 v228, 16, v30
	v_and_b32_e32 v229, 0xffff0000, v30
	v_lshlrev_b32_e32 v230, 16, v34
	v_and_b32_e32 v231, 0xffff0000, v34
	v_lshlrev_b32_e32 v232, 16, v38
	v_and_b32_e32 v233, 0xffff0000, v38
	s_waitcnt lgkmcnt(6)
	v_mul_f32_e32 v234, v228, v219
	v_mul_f32_e32 v235, v232, v219
	v_mul_f32_e32 v236, v229, v221
	v_mul_f32_e32 v237, v233, v221
	v_mul_f32_e32 v238, v228, v218
	v_mul_f32_e32 v239, v232, v218
	v_mul_f32_e32 v240, v229, v220
	v_mul_f32_e32 v241, v233, v220
	v_fma_f32 v228, v226, v219, v238
	v_fma_f32 v232, v230, v219, v239
	v_fma_f32 v229, v227, v221, v240
	v_fma_f32 v233, v231, v221, v241
	v_fma_f32 v226, v226, v218, -v234
	v_fma_f32 v230, v230, v218, -v235
	v_fma_f32 v227, v227, v220, -v236
	v_fma_f32 v231, v231, v220, -v237
	v_mul_f32_e32 v228, v188, v228
	v_mul_f32_e32 v229, v188, v229
	v_mul_f32_e32 v232, v189, v232
	v_mul_f32_e32 v233, v189, v233
	v_mul_f32_e32 v226, v188, v226
	v_mul_f32_e32 v227, v188, v227
	v_mul_f32_e32 v230, v189, v230
	v_mul_f32_e32 v231, v189, v231
	v_cvt_pk_bf16_f32 v30, v228, v229
	v_cvt_pk_bf16_f32 v38, v232, v233
	v_cvt_pk_bf16_f32 v26, v226, v227
	v_cvt_pk_bf16_f32 v34, v230, v231
	v_lshlrev_b32_e32 v226, 16, v27
	v_and_b32_e32 v227, 0xffff0000, v27
	v_lshlrev_b32_e32 v228, 16, v31
	v_and_b32_e32 v229, 0xffff0000, v31
	v_lshlrev_b32_e32 v230, 16, v35
	v_and_b32_e32 v231, 0xffff0000, v35
	v_lshlrev_b32_e32 v232, 16, v39
	v_and_b32_e32 v233, 0xffff0000, v39
	s_waitcnt lgkmcnt(5)
	v_mul_f32_e32 v234, v228, v223
	v_mul_f32_e32 v235, v232, v223
	v_mul_f32_e32 v236, v229, v225
	v_mul_f32_e32 v237, v233, v225
	v_mul_f32_e32 v238, v228, v222
	v_mul_f32_e32 v239, v232, v222
	v_mul_f32_e32 v240, v229, v224
	v_mul_f32_e32 v241, v233, v224
	v_fma_f32 v228, v226, v223, v238
	v_fma_f32 v232, v230, v223, v239
	v_fma_f32 v229, v227, v225, v240
	v_fma_f32 v233, v231, v225, v241
	v_fma_f32 v226, v226, v222, -v234
	v_fma_f32 v230, v230, v222, -v235
	v_fma_f32 v227, v227, v224, -v236
	v_fma_f32 v231, v231, v224, -v237
	v_mul_f32_e32 v228, v188, v228
	v_mul_f32_e32 v229, v188, v229
	v_mul_f32_e32 v232, v189, v232
	v_mul_f32_e32 v233, v189, v233
	v_mul_f32_e32 v226, v188, v226
	v_mul_f32_e32 v227, v188, v227
	v_mul_f32_e32 v230, v189, v230
	v_mul_f32_e32 v231, v189, v231
	v_cvt_pk_bf16_f32 v31, v228, v229
	v_cvt_pk_bf16_f32 v39, v232, v233
	v_cvt_pk_bf16_f32 v27, v226, v227
	v_cvt_pk_bf16_f32 v35, v230, v231
	v_add_u32_e32 v248, v167, v129
	ds_write_b128 v248, v[24:27]
	ds_write_b128 v248, v[28:31] offset:128
	ds_write_b128 v170, v[32:35] offset:33792
	ds_write_b128 v170, v[36:39] offset:33920
	s_waitcnt vmcnt(0)
	ds_write_b128 v171, v[40:43]
	s_waitcnt lgkmcnt(0)
	s_branch .Lret_bar1
.LBB0_340:
	v_cvt_pk_bf16_f32 v104, v104, v105
	v_cvt_pk_bf16_f32 v105, v106, v107
	s_nop 2
	v_add_u32_e32 v106, s22, v134
	ds_write_b64 v106, v[104:105]
	ds_read_b64 v[104:105], v131
	ds_read_b64 v[106:107], v131 offset:32
	v_add_u32_e32 v139, 0x2000, v131
	v_add_u32_e32 v141, 0x4000, v131
	v_add_u32_e32 v143, 0x6000, v131
	ds_read_b64 v[108:109], v139 offset:256
	ds_read_b64 v[110:111], v139 offset:288
	ds_read_b64 v[112:113], v141 offset:512
	ds_read_b64 v[114:115], v141 offset:544
	v_cvt_pk_bf16_f32 v116, v100, v101
	v_cvt_pk_bf16_f32 v117, v102, v103
	v_cvt_pk_bf16_f32 v118, v88, v89
	v_cvt_pk_bf16_f32 v119, v90, v91
	ds_read_b64 v[120:121], v143 offset:768
	ds_read_b64 v[122:123], v143 offset:800
	s_lshl_b32 s13, s41, 6
	s_and_b64 s[16:17], s[16:17], exec
	s_cselect_b32 s12, s33, s1
	s_add_i32 s13, s13, s12
	s_waitcnt lgkmcnt(6)
	v_mfma_f32_16x16x32_bf16 v[104:107], v[116:119], v[104:107], 0
	v_add_u32_e32 v4, s47, v160
	v_mov_b64_e32 v[20:21], s[26:27]
	v_mad_i64_i32 v[22:23], s[42:43], v4, s3, v[20:21]
	v_lshl_add_u64 v[4:5], v[22:23], 0, s[90:91]
	s_mov_b32 s67, s91
	v_lshl_add_u64 v[12:13], v[4:5], 0, v[174:175]
	v_lshl_add_u64 v[22:23], v[22:23], 0, s[66:67]
	ds_read_b64 v[124:125], v131 offset:64
	ds_read_b64 v[126:127], v131 offset:96
	s_waitcnt lgkmcnt(6)
	v_mfma_f32_16x16x32_bf16 v[108:111], v[116:119], v[108:111], 0
	s_mov_b32 s15, s91
	v_add_co_u32_e32 v16, vcc, s21, v12
	v_lshl_add_u64 v[22:23], v[22:23], 0, s[14:15]
	v_mov_b32_e32 v132, v140
	v_mov_b32_e32 v133, v175
	v_add_u32_e32 v24, s47, v161
	v_addc_co_u32_e32 v17, vcc, 0, v13, vcc
	v_lshl_add_u64 v[22:23], v[22:23], 0, v[132:133]
	ds_read_b64 v[148:149], v139 offset:320
	ds_read_b64 v[150:151], v139 offset:352
	s_waitcnt lgkmcnt(6)
	v_mfma_f32_16x16x32_bf16 v[112:115], v[116:119], v[112:115], 0
	v_mad_i64_i32 v[36:37], s[42:43], v24, s3, v[20:21]
	v_add_co_u32_e32 v22, vcc, s18, v22
	v_lshl_add_u64 v[20:21], v[36:37], 0, s[90:91]
	s_nop 0
	v_addc_co_u32_e32 v23, vcc, 0, v23, vcc
	v_lshl_add_u64 v[28:29], v[20:21], 0, v[174:175]
	v_lshl_add_u64 v[36:37], v[36:37], 0, s[66:67]
	ds_read_b64 v[152:153], v141 offset:576
	ds_read_b64 v[154:155], v141 offset:608
	s_waitcnt lgkmcnt(6)
	v_mfma_f32_16x16x32_bf16 v[116:119], v[116:119], v[120:123], 0
	v_add_co_u32_e32 v38, vcc, 0x1000, v28
	v_lshl_add_u64 v[36:37], v[36:37], 0, s[14:15]
	s_nop 0
	v_addc_co_u32_e32 v39, vcc, 0, v29, vcc
	v_lshl_add_u64 v[36:37], v[36:37], 0, v[132:133]
	v_add_co_u32_e32 v40, vcc, 0x2000, v36
	s_nop 1
	v_addc_co_u32_e32 v41, vcc, 0, v37, vcc
	v_cvt_pk_bf16_f32 v120, v84, v85
	v_cvt_pk_bf16_f32 v121, v86, v87
	v_cvt_pk_bf16_f32 v122, v80, v81
	v_cvt_pk_bf16_f32 v123, v82, v83
	ds_read_b64 v[156:157], v143 offset:832
	ds_read_b64 v[158:159], v143 offset:864
	s_waitcnt lgkmcnt(6)
	v_mfma_f32_16x16x32_bf16 v[104:107], v[120:123], v[124:127], v[104:107]
	global_load_dwordx4 v[4:7], v[12:13], off
	ds_read_b64 v[124:125], v131 offset:128
	ds_read_b64 v[126:127], v131 offset:160
	s_waitcnt lgkmcnt(6)
	v_mfma_f32_16x16x32_bf16 v[108:111], v[120:123], v[148:151], v[108:111]
	ds_read_b64 v[148:149], v139 offset:384
	ds_read_b64 v[150:151], v139 offset:416
	s_waitcnt lgkmcnt(6)
	v_mfma_f32_16x16x32_bf16 v[112:115], v[120:123], v[152:155], v[112:115]
	global_load_dwordx4 v[8:11], v[12:13], off offset:128
	ds_read_b64 v[152:153], v141 offset:640
	ds_read_b64 v[154:155], v141 offset:672
	s_waitcnt lgkmcnt(6)
	v_mfma_f32_16x16x32_bf16 v[116:119], v[120:123], v[156:159], v[116:119]
	v_cvt_pk_bf16_f32 v120, v76, v77
	v_cvt_pk_bf16_f32 v121, v78, v79
	v_cvt_pk_bf16_f32 v122, v72, v73
	v_cvt_pk_bf16_f32 v123, v74, v75
	ds_read_b64 v[156:157], v143 offset:896
	ds_read_b64 v[158:159], v143 offset:928
	s_waitcnt lgkmcnt(6)
	v_mfma_f32_16x16x32_bf16 v[104:107], v[120:123], v[124:127], v[104:107]
	global_load_dwordx4 v[12:15], v[16:17], off
	ds_read_b64 v[124:125], v131 offset:192
	ds_read_b64 v[126:127], v131 offset:224
	s_waitcnt lgkmcnt(6)
	v_mfma_f32_16x16x32_bf16 v[108:111], v[120:123], v[148:151], v[108:111]
	ds_read_b64 v[148:149], v139 offset:448
	ds_read_b64 v[150:151], v139 offset:480
	s_waitcnt lgkmcnt(6)
	v_mfma_f32_16x16x32_bf16 v[112:115], v[120:123], v[152:155], v[112:115]
	global_load_dwordx4 v[16:19], v[16:17], off offset:128
	ds_read_b64 v[152:153], v141 offset:704
	ds_read_b64 v[154:155], v141 offset:736
	s_waitcnt lgkmcnt(6)
	v_mfma_f32_16x16x32_bf16 v[116:119], v[120:123], v[156:159], v[116:119]
	v_cvt_pk_bf16_f32 v120, v68, v69
	v_cvt_pk_bf16_f32 v121, v70, v71
	v_cvt_pk_bf16_f32 v122, v64, v65
	v_cvt_pk_bf16_f32 v123, v66, v67
	ds_read_b64 v[156:157], v143 offset:960
	ds_read_b64 v[158:159], v143 offset:992
	s_waitcnt lgkmcnt(6)
	v_mfma_f32_16x16x32_bf16 v[104:107], v[120:123], v[124:127], v[104:107]
	global_load_dwordx4 v[20:23], v[22:23], off
	ds_read_b64 v[124:125], v131 offset:256
	ds_read_b64 v[126:127], v131 offset:288
	s_waitcnt lgkmcnt(6)
	v_mfma_f32_16x16x32_bf16 v[108:111], v[120:123], v[148:151], v[108:111]
	ds_read_b64 v[148:149], v139 offset:512
	ds_read_b64 v[150:151], v139 offset:544
	s_waitcnt lgkmcnt(6)
	v_mfma_f32_16x16x32_bf16 v[112:115], v[120:123], v[152:155], v[112:115]
	global_load_dwordx4 v[24:27], v[28:29], off
	ds_read_b64 v[152:153], v141 offset:768
	ds_read_b64 v[154:155], v141 offset:800
	s_waitcnt lgkmcnt(6)
	v_mfma_f32_16x16x32_bf16 v[116:119], v[120:123], v[156:159], v[116:119]
	v_cvt_pk_bf16_f32 v120, v60, v61
	v_cvt_pk_bf16_f32 v121, v62, v63
	v_cvt_pk_bf16_f32 v122, v56, v57
	v_cvt_pk_bf16_f32 v123, v58, v59
	ds_read_b64 v[156:157], v143 offset:1024
	ds_read_b64 v[158:159], v143 offset:1056
	s_waitcnt lgkmcnt(6)
	v_mfma_f32_16x16x32_bf16 v[104:107], v[120:123], v[124:127], v[104:107]
	global_load_dwordx4 v[28:31], v[28:29], off offset:128
	ds_read_b64 v[124:125], v131 offset:320
	ds_read_b64 v[126:127], v131 offset:352
	s_waitcnt lgkmcnt(6)
	v_mfma_f32_16x16x32_bf16 v[108:111], v[120:123], v[148:151], v[108:111]
	ds_read_b64 v[148:149], v139 offset:576
	ds_read_b64 v[150:151], v139 offset:608
	s_waitcnt lgkmcnt(6)
	v_mfma_f32_16x16x32_bf16 v[112:115], v[120:123], v[152:155], v[112:115]
	global_load_dwordx4 v[32:35], v[38:39], off
	ds_read_b64 v[152:153], v141 offset:832
	ds_read_b64 v[154:155], v141 offset:864
	s_waitcnt lgkmcnt(6)
	v_mfma_f32_16x16x32_bf16 v[116:119], v[120:123], v[156:159], v[116:119]
	v_cvt_pk_bf16_f32 v120, v52, v53
	v_cvt_pk_bf16_f32 v121, v54, v55
	v_cvt_pk_bf16_f32 v122, v48, v49
	v_cvt_pk_bf16_f32 v123, v50, v51
	ds_read_b64 v[156:157], v143 offset:1088
	ds_read_b64 v[158:159], v143 offset:1120
	s_waitcnt lgkmcnt(6)
	v_mfma_f32_16x16x32_bf16 v[104:107], v[120:123], v[124:127], v[104:107]
	global_load_dwordx4 v[36:39], v[38:39], off offset:128
	ds_read_b64 v[124:125], v131 offset:384
	ds_read_b64 v[126:127], v131 offset:416
	s_waitcnt lgkmcnt(6)
	v_mfma_f32_16x16x32_bf16 v[108:111], v[120:123], v[148:151], v[108:111]
	ds_read_b64 v[148:149], v139 offset:640
	ds_read_b64 v[150:151], v139 offset:672
	s_waitcnt lgkmcnt(6)
	v_mfma_f32_16x16x32_bf16 v[112:115], v[120:123], v[152:155], v[112:115]
	global_load_dwordx4 v[40:43], v[40:41], off
	ds_read_b64 v[152:153], v141 offset:896
	ds_read_b64 v[154:155], v141 offset:928
	s_waitcnt lgkmcnt(6)
	v_mfma_f32_16x16x32_bf16 v[116:119], v[120:123], v[156:159], v[116:119]
	v_cvt_pk_bf16_f32 v120, v44, v45
	v_cvt_pk_bf16_f32 v121, v46, v47
	v_cvt_pk_bf16_f32 v122, v0, v1
	v_cvt_pk_bf16_f32 v123, v2, v3
	ds_read_b64 v[156:157], v143 offset:1152
	ds_read_b64 v[158:159], v143 offset:1184
	s_waitcnt lgkmcnt(6)
	v_mfma_f32_16x16x32_bf16 v[104:107], v[120:123], v[124:127], v[104:107]
	ds_read_b64 v[124:125], v131 offset:448
	ds_read_b64 v[126:127], v131 offset:480
	s_waitcnt lgkmcnt(6)
	v_mfma_f32_16x16x32_bf16 v[108:111], v[120:123], v[148:151], v[108:111]
	ds_read_b64 v[148:149], v139 offset:704
	ds_read_b64 v[150:151], v139 offset:736
	s_waitcnt lgkmcnt(6)
	v_mfma_f32_16x16x32_bf16 v[112:115], v[120:123], v[152:155], v[112:115]
	ds_read_b64 v[152:153], v141 offset:960
	ds_read_b64 v[154:155], v141 offset:992
	s_waitcnt lgkmcnt(6)
	v_mfma_f32_16x16x32_bf16 v[156:159], v[120:123], v[156:159], v[116:119]
	v_cvt_pk_bf16_f32 v180, v92, v93
	v_cvt_pk_bf16_f32 v181, v94, v95
	v_cvt_pk_bf16_f32 v182, v96, v97
	v_cvt_pk_bf16_f32 v183, v98, v99
	ds_read_b64 v[190:191], v143 offset:1216
	ds_read_b64 v[192:193], v143 offset:1248
	s_waitcnt lgkmcnt(6)
	v_mfma_f32_16x16x32_bf16 v[124:127], v[180:183], v[124:127], v[104:107]
	s_waitcnt lgkmcnt(4)
	v_mfma_f32_16x16x32_bf16 v[120:123], v[180:183], v[148:151], v[108:111]
	s_waitcnt lgkmcnt(2)
	v_mfma_f32_16x16x32_bf16 v[116:119], v[180:183], v[152:155], v[112:115]
	s_waitcnt lgkmcnt(0)
	v_mfma_f32_16x16x32_bf16 v[108:111], v[180:183], v[190:193], v[156:159]
	ds_read_b64_tr_b16 v[150:151], v135 offset:42496
	ds_read_b64_tr_b16 v[148:149], v135 offset:33792
	ds_read_b64_tr_b16 v[112:113], v185
	ds_read_b64_tr_b16 v[114:115], v185 offset:4608
	ds_read_b64_tr_b16 v[104:105], v185 offset:9216
	ds_read_b64_tr_b16 v[106:107], v185 offset:13824
	ds_read_b64_tr_b16 v[154:155], v135 offset:42528
	ds_read_b64_tr_b16 v[152:153], v135 offset:33824
	ds_read_b64_tr_b16 v[156:157], v135 offset:51200
	ds_read_b64_tr_b16 v[158:159], v135 offset:59904
	ds_read_b64_tr_b16 v[182:183], v135 offset:59936
	ds_read_b64_tr_b16 v[180:181], v135 offset:51232
	s_waitcnt lgkmcnt(8)
	v_mfma_f32_16x16x32_bf16 v[100:103], v[148:151], v[112:115], v[100:103]
	ds_read_b64_tr_b16 v[148:149], v135 offset:33856
	ds_read_b64_tr_b16 v[150:151], v135 offset:42560
	s_waitcnt lgkmcnt(4)
	v_mfma_f32_16x16x32_bf16 v[100:103], v[156:159], v[104:107], v[100:103]
	ds_read_b64_tr_b16 v[156:157], v135 offset:51264
	ds_read_b64_tr_b16 v[158:159], v135 offset:59968
	v_mfma_f32_16x16x32_bf16 v[88:91], v[152:155], v[112:115], v[88:91]
	v_mov_b32_e32 v143, v142
	s_nop 3
	v_pk_mul_f32 v[102:103], v[142:143], v[102:103]
	v_pk_mul_f32 v[100:101], v[144:145], v[100:101]
	ds_read_b64_tr_b16 v[152:153], v135 offset:33888
	ds_read_b64_tr_b16 v[154:155], v135 offset:42592
	s_waitcnt lgkmcnt(6)
	v_mfma_f32_16x16x32_bf16 v[88:91], v[180:183], v[104:107], v[88:91]
	ds_read_b64_tr_b16 v[180:181], v135 offset:51296
	ds_read_b64_tr_b16 v[182:183], v135 offset:60000
	s_waitcnt lgkmcnt(6)
	v_mfma_f32_16x16x32_bf16 v[84:87], v[148:151], v[112:115], v[84:87]
	s_nop 3
	v_mul_f32_e64 v90, v142, v90
	v_mul_f32_e64 v91, v143, v91
	v_pk_mul_f32 v[88:89], v[144:145], v[88:89]
	ds_read_b64_tr_b16 v[148:149], v135 offset:33920
	ds_read_b64_tr_b16 v[150:151], v135 offset:42624
	s_waitcnt lgkmcnt(6)
	v_mfma_f32_16x16x32_bf16 v[84:87], v[156:159], v[104:107], v[84:87]
	ds_read_b64_tr_b16 v[156:157], v135 offset:51328
	ds_read_b64_tr_b16 v[158:159], v135 offset:60032
	s_waitcnt lgkmcnt(6)
	v_mfma_f32_16x16x32_bf16 v[80:83], v[152:155], v[112:115], v[80:83]
	s_nop 3
	v_mul_f32_e64 v86, v142, v86
	v_mul_f32_e64 v87, v143, v87
	v_pk_mul_f32 v[84:85], v[144:145], v[84:85]
	ds_read_b64_tr_b16 v[152:153], v135 offset:33952
	ds_read_b64_tr_b16 v[154:155], v135 offset:42656
	s_waitcnt lgkmcnt(6)
	v_mfma_f32_16x16x32_bf16 v[80:83], v[180:183], v[104:107], v[80:83]
	ds_read_b64_tr_b16 v[180:181], v135 offset:51360
	ds_read_b64_tr_b16 v[182:183], v135 offset:60064
	s_waitcnt lgkmcnt(6)
	v_mfma_f32_16x16x32_bf16 v[76:79], v[148:151], v[112:115], v[76:79]
	s_nop 3
	v_mul_f32_e64 v82, v142, v82
	v_mul_f32_e64 v83, v143, v83
	v_pk_mul_f32 v[80:81], v[144:145], v[80:81]
	ds_read_b64_tr_b16 v[148:149], v135 offset:33984
	ds_read_b64_tr_b16 v[150:151], v135 offset:42688
	s_waitcnt lgkmcnt(6)
	v_mfma_f32_16x16x32_bf16 v[76:79], v[156:159], v[104:107], v[76:79]
	ds_read_b64_tr_b16 v[156:157], v135 offset:51392
	ds_read_b64_tr_b16 v[158:159], v135 offset:60096
	s_waitcnt lgkmcnt(6)
	v_mfma_f32_16x16x32_bf16 v[72:75], v[152:155], v[112:115], v[72:75]
	s_nop 3
	v_mul_f32_e64 v78, v142, v78
	v_mul_f32_e64 v79, v143, v79
	v_pk_mul_f32 v[76:77], v[144:145], v[76:77]
	ds_read_b64_tr_b16 v[152:153], v135 offset:34016
	ds_read_b64_tr_b16 v[154:155], v135 offset:42720
	s_waitcnt lgkmcnt(6)
	v_mfma_f32_16x16x32_bf16 v[72:75], v[180:183], v[104:107], v[72:75]
	ds_read_b64_tr_b16 v[180:181], v135 offset:51424
	ds_read_b64_tr_b16 v[182:183], v135 offset:60128
	s_waitcnt lgkmcnt(6)
	v_mfma_f32_16x16x32_bf16 v[68:71], v[148:151], v[112:115], v[68:71]
	s_nop 3
	v_mul_f32_e64 v74, v142, v74
	v_mul_f32_e64 v75, v143, v75
	v_pk_mul_f32 v[72:73], v[144:145], v[72:73]
	ds_read_b64_tr_b16 v[148:149], v135 offset:34048
	ds_read_b64_tr_b16 v[150:151], v135 offset:42752
	s_waitcnt lgkmcnt(6)
	v_mfma_f32_16x16x32_bf16 v[68:71], v[156:159], v[104:107], v[68:71]
	ds_read_b64_tr_b16 v[156:157], v135 offset:51456
	ds_read_b64_tr_b16 v[158:159], v135 offset:60160
	s_waitcnt lgkmcnt(6)
	v_mfma_f32_16x16x32_bf16 v[64:67], v[152:155], v[112:115], v[64:67]
	s_nop 3
	v_mul_f32_e64 v70, v142, v70
	v_mul_f32_e64 v71, v143, v71
	v_pk_mul_f32 v[68:69], v[144:145], v[68:69]
	ds_read_b64_tr_b16 v[152:153], v135 offset:34080
	ds_read_b64_tr_b16 v[154:155], v135 offset:42784
	s_waitcnt lgkmcnt(6)
	v_mfma_f32_16x16x32_bf16 v[64:67], v[180:183], v[104:107], v[64:67]
	ds_read_b64_tr_b16 v[180:181], v135 offset:51488
	ds_read_b64_tr_b16 v[182:183], v135 offset:60192
	s_waitcnt lgkmcnt(6)
	v_mfma_f32_16x16x32_bf16 v[60:63], v[148:151], v[112:115], v[60:63]
	s_nop 3
	v_mul_f32_e64 v66, v142, v66
	v_mul_f32_e64 v67, v143, v67
	v_pk_mul_f32 v[64:65], v[144:145], v[64:65]
	ds_read_b64_tr_b16 v[148:149], v135 offset:34112
	ds_read_b64_tr_b16 v[150:151], v135 offset:42816
	s_waitcnt lgkmcnt(6)
	v_mfma_f32_16x16x32_bf16 v[60:63], v[156:159], v[104:107], v[60:63]
	ds_read_b64_tr_b16 v[156:157], v135 offset:51520
	ds_read_b64_tr_b16 v[158:159], v135 offset:60224
	s_waitcnt lgkmcnt(6)
	v_mfma_f32_16x16x32_bf16 v[56:59], v[152:155], v[112:115], v[56:59]
	s_nop 3
	v_mul_f32_e64 v62, v142, v62
	v_mul_f32_e64 v63, v143, v63
	v_pk_mul_f32 v[60:61], v[144:145], v[60:61]
	ds_read_b64_tr_b16 v[152:153], v135 offset:34144
	ds_read_b64_tr_b16 v[154:155], v135 offset:42848
	s_waitcnt lgkmcnt(6)
	v_mfma_f32_16x16x32_bf16 v[56:59], v[180:183], v[104:107], v[56:59]
	ds_read_b64_tr_b16 v[180:181], v135 offset:51552
	ds_read_b64_tr_b16 v[182:183], v135 offset:60256
	s_waitcnt lgkmcnt(6)
	v_mfma_f32_16x16x32_bf16 v[52:55], v[148:151], v[112:115], v[52:55]
	s_nop 3
	v_mul_f32_e64 v58, v142, v58
	v_mul_f32_e64 v59, v143, v59
	v_pk_mul_f32 v[56:57], v[144:145], v[56:57]
	ds_read_b64_tr_b16 v[148:149], v135 offset:34176
	ds_read_b64_tr_b16 v[150:151], v135 offset:42880
	s_waitcnt lgkmcnt(6)
	v_mfma_f32_16x16x32_bf16 v[52:55], v[156:159], v[104:107], v[52:55]
	ds_read_b64_tr_b16 v[156:157], v135 offset:51584
	ds_read_b64_tr_b16 v[158:159], v135 offset:60288
	s_waitcnt lgkmcnt(6)
	v_mfma_f32_16x16x32_bf16 v[48:51], v[152:155], v[112:115], v[48:51]
	s_nop 3
	v_mul_f32_e64 v54, v142, v54
	v_mul_f32_e64 v55, v143, v55
	v_pk_mul_f32 v[52:53], v[144:145], v[52:53]
	ds_read_b64_tr_b16 v[152:153], v135 offset:34208
	ds_read_b64_tr_b16 v[154:155], v135 offset:42912
	s_waitcnt lgkmcnt(6)
	v_mfma_f32_16x16x32_bf16 v[48:51], v[180:183], v[104:107], v[48:51]
	ds_read_b64_tr_b16 v[180:181], v135 offset:51616
	ds_read_b64_tr_b16 v[182:183], v135 offset:60320
	s_waitcnt lgkmcnt(6)
	v_mfma_f32_16x16x32_bf16 v[44:47], v[148:151], v[112:115], v[44:47]
	s_nop 3
	v_mul_f32_e64 v50, v142, v50
	v_mul_f32_e64 v51, v143, v51
	v_pk_mul_f32 v[48:49], v[144:145], v[48:49]
	ds_read_b64_tr_b16 v[148:149], v135 offset:34240
	ds_read_b64_tr_b16 v[150:151], v135 offset:42944
	s_waitcnt lgkmcnt(6)
	v_mfma_f32_16x16x32_bf16 v[44:47], v[156:159], v[104:107], v[44:47]
	ds_read_b64_tr_b16 v[156:157], v135 offset:51648
	ds_read_b64_tr_b16 v[158:159], v135 offset:60352
	s_waitcnt lgkmcnt(6)
	v_mfma_f32_16x16x32_bf16 v[0:3], v[152:155], v[112:115], v[0:3]
	s_nop 3
	v_mul_f32_e64 v46, v142, v46
	v_mul_f32_e64 v47, v143, v47
	v_pk_mul_f32 v[44:45], v[144:145], v[44:45]
	ds_read_b64_tr_b16 v[152:153], v135 offset:34272
	ds_read_b64_tr_b16 v[154:155], v135 offset:42976
	s_waitcnt lgkmcnt(6)
	v_mfma_f32_16x16x32_bf16 v[0:3], v[180:183], v[104:107], v[0:3]
	ds_read_b64_tr_b16 v[180:181], v135 offset:51680
	ds_read_b64_tr_b16 v[182:183], v135 offset:60384
	s_waitcnt lgkmcnt(6)
	v_mfma_f32_16x16x32_bf16 v[92:95], v[148:151], v[112:115], v[92:95]
	s_nop 3
	v_mul_f32_e64 v2, v142, v2
	v_mul_f32_e64 v3, v143, v3
	v_pk_mul_f32 v[0:1], v[144:145], v[0:1]
	s_waitcnt lgkmcnt(4)
	v_mfma_f32_16x16x32_bf16 v[92:95], v[156:159], v[104:107], v[92:95]
	s_waitcnt lgkmcnt(2)
	v_mfma_f32_16x16x32_bf16 v[96:99], v[152:155], v[112:115], v[96:99]
	s_nop 5
	v_mul_f32_e64 v94, v142, v94
	v_mul_f32_e64 v95, v143, v95
	v_pk_mul_f32 v[92:93], v[144:145], v[92:93]
	s_waitcnt lgkmcnt(0)
	v_mfma_f32_16x16x32_bf16 v[96:99], v[180:183], v[104:107], v[96:99]
	s_barrier
	s_ashr_i32 s12, s13, 31
	s_add_u32 s16, s13, s19
	s_addc_u32 s17, s12, 0
	s_lshl_b64 s[16:17], s[16:17], 13
	s_mov_b32 s12, 0x20000
	v_lshl_add_u64 v[250:251], v[146:147], 0, s[16:17]
	s_add_i32 s40, s40, 1
	v_add_co_u32_e64 v226, s[16:17], s40, 4
	s_nop 0
	v_readfirstlane_b32 s13, v226
	s_and_b64 vcc, s[16:17], exec
	s_cselect_b32 s41, s13, s40
	s_cselect_b32 s42, 3, 31
	s_sub_i32 s67, s42, s41
	s_and_b64 s[42:43], exec, s[74:75]
	s_cselect_b32 s41, s41, s67
	s_and_b64 vcc, s[16:17], exec
	s_cselect_b64 s[44:45], -1, s[38:39]
	s_cselect_b32 s46, 64, s41
	v_mov_b32_e32 v242, s46
	v_cndmask_b32_e64 v242, v160, v242, s[44:45]
	v_and_b32_e32 v226, 0xff, v174
	v_lshlrev_b32_e32 v226, 2, v226
	v_lshl_add_u32 v242, v242, 9, v226
	v_add_u32_e32 v242, 0x18000, v242
	ds_read_b128 v[194:197], v242
	ds_read_b128 v[198:201], v242 offset:16
	ds_read_b128 v[202:205], v242 offset:32
	ds_read_b128 v[206:209], v242 offset:48
	s_waitcnt vmcnt(6)
	v_lshlrev_b32_e32 v226, 16, v4
	v_and_b32_e32 v227, 0xffff0000, v4
	v_lshlrev_b32_e32 v228, 16, v8
	ds_read_b64 v[148:149], v186
	v_and_b32_e32 v229, 0xffff0000, v8
	v_lshlrev_b32_e32 v230, 16, v12
	v_and_b32_e32 v231, 0xffff0000, v12
	ds_read_b64 v[150:151], v186 offset:32
	v_lshlrev_b32_e32 v232, 16, v16
	v_and_b32_e32 v233, 0xffff0000, v16
	s_waitcnt lgkmcnt(5)
	ds_read_b64 v[152:153], v186 offset:64
	v_mul_f32_e32 v234, v228, v195
	v_mul_f32_e32 v235, v232, v195
	v_mul_f32_e32 v236, v229, v197
	ds_read_b64 v[154:155], v186 offset:96
	v_mul_f32_e32 v237, v233, v197
	v_mul_f32_e32 v238, v228, v194
	v_mul_f32_e32 v239, v232, v194
	v_add_u32_e32 v139, 0x800, v186
	v_mul_f32_e32 v240, v229, v196
	v_mul_f32_e32 v241, v233, v196
	v_fma_f32 v228, v226, v195, v238
	ds_read_b64 v[156:157], v139 offset:256
	v_fma_f32 v232, v230, v195, v239
	v_fma_f32 v229, v227, v197, v240
	v_fma_f32 v233, v231, v197, v241
	ds_read_b64 v[158:159], v139 offset:288
	v_fma_f32 v226, v226, v194, -v234
	v_fma_f32 v230, v230, v194, -v235
	v_fma_f32 v227, v227, v196, -v236
	ds_read_b64 v[180:181], v139 offset:320
	v_fma_f32 v231, v231, v196, -v237
	v_mul_f32_e32 v228, v137, v228
	v_mul_f32_e32 v229, v137, v229
	ds_read_b64 v[182:183], v139 offset:352
	v_mul_f32_e32 v232, v179, v232
	v_mul_f32_e32 v233, v179, v233
	v_mul_f32_e32 v226, v137, v226
	v_add_u32_e32 v139, 0x1000, v186
	v_mul_f32_e32 v227, v137, v227
	v_mul_f32_e32 v230, v179, v230
	v_mul_f32_e32 v231, v179, v231
	ds_read_b64 v[190:191], v139 offset:512
	v_cvt_pk_bf16_f32 v8, v228, v229
	v_cvt_pk_bf16_f32 v16, v232, v233
	v_cvt_pk_bf16_f32 v4, v226, v227
	ds_read_b64 v[192:193], v139 offset:544
	v_cvt_pk_bf16_f32 v12, v230, v231
	v_lshlrev_b32_e32 v226, 16, v5
	v_and_b32_e32 v227, 0xffff0000, v5
	v_pk_mul_f32 v[98:99], v[142:143], v[98:99]
	v_lshlrev_b32_e32 v228, 16, v9
	v_and_b32_e32 v229, 0xffff0000, v9
	v_lshlrev_b32_e32 v230, 16, v13
	v_pk_mul_f32 v[96:97], v[144:145], v[96:97]
	v_and_b32_e32 v231, 0xffff0000, v13
	v_lshlrev_b32_e32 v232, 16, v17
	v_and_b32_e32 v233, 0xffff0000, v17
	s_waitcnt lgkmcnt(8)
	s_waitcnt lgkmcnt(12)
	v_mul_f32_e32 v234, v228, v199
	v_mul_f32_e32 v235, v232, v199
	v_mfma_f32_16x16x32_bf16 v[124:127], v[112:115], v[148:151], v[124:127]
	v_mul_f32_e32 v236, v229, v201
	v_mul_f32_e32 v237, v233, v201
	v_mul_f32_e32 v238, v228, v198
	ds_read_b64 v[148:149], v139 offset:576
	v_mul_f32_e32 v239, v232, v198
	v_mul_f32_e32 v240, v229, v200
	v_mul_f32_e32 v241, v233, v200
	ds_read_b64 v[150:151], v139 offset:608
	v_fma_f32 v228, v226, v199, v238
	v_fma_f32 v232, v230, v199, v239
	v_fma_f32 v229, v227, v201, v240
	s_waitcnt lgkmcnt(8)
	v_fma_f32 v233, v231, v201, v241
	v_fma_f32 v226, v226, v198, -v234
	v_fma_f32 v230, v230, v198, -v235
	v_mfma_f32_16x16x32_bf16 v[124:127], v[104:107], v[152:155], v[124:127]
	v_fma_f32 v227, v227, v200, -v236
	v_fma_f32 v231, v231, v200, -v237
	v_mul_f32_e32 v228, v137, v228
	v_add_u32_e32 v139, 0x1800, v186
	v_mul_f32_e32 v229, v137, v229
	v_mul_f32_e32 v232, v179, v232
	v_mul_f32_e32 v233, v179, v233
	ds_read_b64 v[152:153], v139 offset:768
	v_mul_f32_e32 v226, v137, v226
	v_mul_f32_e32 v227, v137, v227
	v_mul_f32_e32 v230, v179, v230
	ds_read_b64 v[154:155], v139 offset:800
	v_mul_f32_e32 v231, v179, v231
	v_cvt_pk_bf16_f32 v9, v228, v229
	v_cvt_pk_bf16_f32 v17, v232, v233
	s_waitcnt lgkmcnt(8)
	v_cvt_pk_bf16_f32 v5, v226, v227
	v_cvt_pk_bf16_f32 v13, v230, v231
	v_lshlrev_b32_e32 v226, 16, v6
	v_mfma_f32_16x16x32_bf16 v[120:123], v[112:115], v[156:159], v[120:123]
	v_and_b32_e32 v227, 0xffff0000, v6
	v_lshlrev_b32_e32 v228, 16, v10
	v_and_b32_e32 v229, 0xffff0000, v10
	ds_read_b64 v[156:157], v139 offset:832
	v_lshlrev_b32_e32 v230, 16, v14
	v_and_b32_e32 v231, 0xffff0000, v14
	v_lshlrev_b32_e32 v232, 16, v18
	ds_read_b64 v[158:159], v139 offset:864
	v_and_b32_e32 v233, 0xffff0000, v18
	s_waitcnt lgkmcnt(15)
	v_mul_f32_e32 v234, v228, v203
	s_waitcnt lgkmcnt(8)
	v_mul_f32_e32 v235, v232, v203
	v_mul_f32_e32 v236, v229, v205
	v_mul_f32_e32 v237, v233, v205
	v_mfma_f32_16x16x32_bf16 v[120:123], v[104:107], v[180:183], v[120:123]
	v_mul_f32_e32 v238, v228, v202
	v_mul_f32_e32 v239, v232, v202
	v_mul_f32_e32 v240, v229, v204
	s_waitcnt lgkmcnt(6)
	v_mul_f32_e32 v241, v233, v204
	v_fma_f32 v228, v226, v203, v238
	v_fma_f32 v232, v230, v203, v239
	v_mfma_f32_16x16x32_bf16 v[116:119], v[112:115], v[190:193], v[116:119]
	v_fma_f32 v229, v227, v205, v240
	v_fma_f32 v233, v231, v205, v241
	v_fma_f32 v226, v226, v202, -v234
	s_waitcnt lgkmcnt(4)
	v_fma_f32 v230, v230, v202, -v235
	v_fma_f32 v227, v227, v204, -v236
	v_fma_f32 v231, v231, v204, -v237
	v_mfma_f32_16x16x32_bf16 v[116:119], v[104:107], v[148:151], v[116:119]
	v_mul_f32_e32 v228, v137, v228
	v_mul_f32_e32 v229, v137, v229
	v_mul_f32_e32 v232, v179, v232
	s_waitcnt lgkmcnt(2)
	v_mul_f32_e32 v233, v179, v233
	v_mul_f32_e32 v226, v137, v226
	v_mul_f32_e32 v227, v137, v227
	v_mfma_f32_16x16x32_bf16 v[108:111], v[112:115], v[152:155], v[108:111]
	v_mul_f32_e32 v230, v179, v230
	v_mul_f32_e32 v231, v179, v231
	v_cvt_pk_bf16_f32 v10, v228, v229
	s_waitcnt lgkmcnt(0)
	v_cvt_pk_bf16_f32 v18, v232, v233
	v_cvt_pk_bf16_f32 v6, v226, v227
	v_cvt_pk_bf16_f32 v14, v230, v231
	v_mfma_f32_16x16x32_bf16 v[104:107], v[104:107], v[156:159], v[108:111]
	v_mov_b32_e32 v243, s46
	v_cndmask_b32_e64 v243, v161, v243, s[44:45]
	v_and_b32_e32 v226, 0xff, v174
	v_lshlrev_b32_e32 v226, 2, v226
	v_lshl_add_u32 v243, v243, 9, v226
	v_add_u32_e32 v243, 0x18000, v243
	ds_read_b128 v[210:213], v243
	ds_read_b128 v[214:217], v243 offset:16
	ds_read_b128 v[218:221], v243 offset:32
	ds_read_b128 v[222:225], v243 offset:48
	v_lshlrev_b32_e32 v226, 16, v7
	v_and_b32_e32 v227, 0xffff0000, v7
	v_lshlrev_b32_e32 v228, 16, v11
	v_and_b32_e32 v229, 0xffff0000, v11
	v_lshlrev_b32_e32 v230, 16, v15
	v_and_b32_e32 v231, 0xffff0000, v15
	v_lshlrev_b32_e32 v232, 16, v19
	v_and_b32_e32 v233, 0xffff0000, v19
	s_waitcnt lgkmcnt(15)
	v_mul_f32_e32 v234, v228, v207
	v_mul_f32_e32 v235, v232, v207
	v_mul_f32_e32 v236, v229, v209
	v_mul_f32_e32 v237, v233, v209
	v_mul_f32_e32 v238, v228, v206
	v_mul_f32_e32 v239, v232, v206
	v_mul_f32_e32 v240, v229, v208
	v_mul_f32_e32 v241, v233, v208
	v_fma_f32 v228, v226, v207, v238
	v_fma_f32 v232, v230, v207, v239
	v_fma_f32 v229, v227, v209, v240
	v_fma_f32 v233, v231, v209, v241
	v_fma_f32 v226, v226, v206, -v234
	v_fma_f32 v230, v230, v206, -v235
	v_fma_f32 v227, v227, v208, -v236
	v_fma_f32 v231, v231, v208, -v237
	v_mul_f32_e32 v228, v137, v228
	v_mul_f32_e32 v229, v137, v229
	v_mul_f32_e32 v232, v179, v232
	v_mul_f32_e32 v233, v179, v233
	v_mul_f32_e32 v226, v137, v226
	v_mul_f32_e32 v227, v137, v227
	v_mul_f32_e32 v230, v179, v230
	v_mul_f32_e32 v231, v179, v231
	v_cvt_pk_bf16_f32 v11, v228, v229
	v_cvt_pk_bf16_f32 v19, v232, v233
	v_cvt_pk_bf16_f32 v7, v226, v227
	v_cvt_pk_bf16_f32 v15, v230, v231
	v_add_u32_e32 v248, v164, v129
	ds_write_b128 v248, v[4:7]
	ds_write_b128 v248, v[8:11] offset:128
	ds_write_b128 v168, v[12:15] offset:33792
	ds_write_b128 v168, v[16:19] offset:33920
	s_waitcnt vmcnt(5)
	ds_write_b128 v169, v[20:23]
	s_waitcnt vmcnt(1)
	v_lshlrev_b32_e32 v226, 16, v24
	v_and_b32_e32 v227, 0xffff0000, v24
	v_lshlrev_b32_e32 v228, 16, v28
	v_and_b32_e32 v229, 0xffff0000, v28
	v_lshlrev_b32_e32 v230, 16, v32
	v_and_b32_e32 v231, 0xffff0000, v32
	v_lshlrev_b32_e32 v232, 16, v36
	v_and_b32_e32 v233, 0xffff0000, v36
	s_waitcnt lgkmcnt(8)
	v_mul_f32_e32 v234, v228, v211
	v_mul_f32_e32 v235, v232, v211
	v_mul_f32_e32 v236, v229, v213
	v_mul_f32_e32 v237, v233, v213
	v_mul_f32_e32 v238, v228, v210
	v_mul_f32_e32 v239, v232, v210
	v_mul_f32_e32 v240, v229, v212
	v_mul_f32_e32 v241, v233, v212
	v_fma_f32 v228, v226, v211, v238
	v_fma_f32 v232, v230, v211, v239
	v_fma_f32 v229, v227, v213, v240
	v_fma_f32 v233, v231, v213, v241
	v_fma_f32 v226, v226, v210, -v234
	v_fma_f32 v230, v230, v210, -v235
	v_fma_f32 v227, v227, v212, -v236
	v_fma_f32 v231, v231, v212, -v237
	v_mul_f32_e32 v228, v188, v228
	v_mul_f32_e32 v229, v188, v229
	v_mul_f32_e32 v232, v189, v232
	v_mul_f32_e32 v233, v189, v233
	v_mul_f32_e32 v226, v188, v226
	v_mul_f32_e32 v227, v188, v227
	v_mul_f32_e32 v230, v189, v230
	v_mul_f32_e32 v231, v189, v231
	v_cvt_pk_bf16_f32 v28, v228, v229
	v_cvt_pk_bf16_f32 v36, v232, v233
	v_cvt_pk_bf16_f32 v24, v226, v227
	v_cvt_pk_bf16_f32 v32, v230, v231
	v_lshlrev_b32_e32 v226, 16, v25
	v_and_b32_e32 v227, 0xffff0000, v25
	v_lshlrev_b32_e32 v228, 16, v29
	v_and_b32_e32 v229, 0xffff0000, v29
	v_lshlrev_b32_e32 v230, 16, v33
	v_and_b32_e32 v231, 0xffff0000, v33
	v_lshlrev_b32_e32 v232, 16, v37
	v_and_b32_e32 v233, 0xffff0000, v37
	s_waitcnt lgkmcnt(7)
	v_mul_f32_e32 v234, v228, v215
	v_mul_f32_e32 v235, v232, v215
	v_mul_f32_e32 v236, v229, v217
	v_mul_f32_e32 v237, v233, v217
	v_mul_f32_e32 v238, v228, v214
	v_mul_f32_e32 v239, v232, v214
	v_mul_f32_e32 v240, v229, v216
	v_mul_f32_e32 v241, v233, v216
	v_fma_f32 v228, v226, v215, v238
	v_fma_f32 v232, v230, v215, v239
	v_fma_f32 v229, v227, v217, v240
	v_fma_f32 v233, v231, v217, v241
	v_fma_f32 v226, v226, v214, -v234
	v_fma_f32 v230, v230, v214, -v235
	v_fma_f32 v227, v227, v216, -v236
	v_fma_f32 v231, v231, v216, -v237
	v_mul_f32_e32 v228, v188, v228
	v_mul_f32_e32 v229, v188, v229
	v_mul_f32_e32 v232, v189, v232
	v_mul_f32_e32 v233, v189, v233
	v_mul_f32_e32 v226, v188, v226
	v_mul_f32_e32 v227, v188, v227
	v_mul_f32_e32 v230, v189, v230
	v_mul_f32_e32 v231, v189, v231
	v_cvt_pk_bf16_f32 v29, v228, v229
	v_cvt_pk_bf16_f32 v37, v232, v233
	v_cvt_pk_bf16_f32 v25, v226, v227
	v_cvt_pk_bf16_f32 v33, v230, v231
	v_lshlrev_b32_e32 v226, 16, v26
	v_and_b32_e32 v227, 0xffff0000, v26
	v_lshlrev_b32_e32 v228, 16, v30
	v_and_b32_e32 v229, 0xffff0000, v30
	v_lshlrev_b32_e32 v230, 16, v34
	v_and_b32_e32 v231, 0xffff0000, v34
	v_lshlrev_b32_e32 v232, 16, v38
	v_and_b32_e32 v233, 0xffff0000, v38
	s_waitcnt lgkmcnt(6)
	v_mul_f32_e32 v234, v228, v219
	v_mul_f32_e32 v235, v232, v219
	v_mul_f32_e32 v236, v229, v221
	v_mul_f32_e32 v237, v233, v221
	v_mul_f32_e32 v238, v228, v218
	v_mul_f32_e32 v239, v232, v218
	v_mul_f32_e32 v240, v229, v220
	v_mul_f32_e32 v241, v233, v220
	v_fma_f32 v228, v226, v219, v238
	v_fma_f32 v232, v230, v219, v239
	v_fma_f32 v229, v227, v221, v240
	v_fma_f32 v233, v231, v221, v241
	v_fma_f32 v226, v226, v218, -v234
	v_fma_f32 v230, v230, v218, -v235
	v_fma_f32 v227, v227, v220, -v236
	v_fma_f32 v231, v231, v220, -v237
	v_mul_f32_e32 v228, v188, v228
	v_mul_f32_e32 v229, v188, v229
	v_mul_f32_e32 v232, v189, v232
	v_mul_f32_e32 v233, v189, v233
	v_mul_f32_e32 v226, v188, v226
	v_mul_f32_e32 v227, v188, v227
	v_mul_f32_e32 v230, v189, v230
	v_mul_f32_e32 v231, v189, v231
	v_cvt_pk_bf16_f32 v30, v228, v229
	v_cvt_pk_bf16_f32 v38, v232, v233
	v_cvt_pk_bf16_f32 v26, v226, v227
	v_cvt_pk_bf16_f32 v34, v230, v231
	v_lshlrev_b32_e32 v226, 16, v27
	v_and_b32_e32 v227, 0xffff0000, v27
	v_lshlrev_b32_e32 v228, 16, v31
	v_and_b32_e32 v229, 0xffff0000, v31
	v_lshlrev_b32_e32 v230, 16, v35
	v_and_b32_e32 v231, 0xffff0000, v35
	v_lshlrev_b32_e32 v232, 16, v39
	v_and_b32_e32 v233, 0xffff0000, v39
	s_waitcnt lgkmcnt(5)
	v_mul_f32_e32 v234, v228, v223
	v_mul_f32_e32 v235, v232, v223
	v_mul_f32_e32 v236, v229, v225
	v_mul_f32_e32 v237, v233, v225
	v_mul_f32_e32 v238, v228, v222
	v_mul_f32_e32 v239, v232, v222
	v_mul_f32_e32 v240, v229, v224
	v_mul_f32_e32 v241, v233, v224
	v_fma_f32 v228, v226, v223, v238
	v_fma_f32 v232, v230, v223, v239
	v_fma_f32 v229, v227, v225, v240
	v_fma_f32 v233, v231, v225, v241
	v_fma_f32 v226, v226, v222, -v234
	v_fma_f32 v230, v230, v222, -v235
	v_fma_f32 v227, v227, v224, -v236
	v_fma_f32 v231, v231, v224, -v237
	v_mul_f32_e32 v228, v188, v228
	v_mul_f32_e32 v229, v188, v229
	v_mul_f32_e32 v232, v189, v232
	v_mul_f32_e32 v233, v189, v233
	v_mul_f32_e32 v226, v188, v226
	v_mul_f32_e32 v227, v188, v227
	v_mul_f32_e32 v230, v189, v230
	v_mul_f32_e32 v231, v189, v231
	v_cvt_pk_bf16_f32 v31, v228, v229
	v_cvt_pk_bf16_f32 v39, v232, v233
	v_cvt_pk_bf16_f32 v27, v226, v227
	v_cvt_pk_bf16_f32 v35, v230, v231
	v_add_u32_e32 v248, v167, v129
	ds_write_b128 v248, v[24:27]
	ds_write_b128 v248, v[28:31] offset:128
	ds_write_b128 v170, v[32:35] offset:33792
	ds_write_b128 v170, v[36:39] offset:33920
	s_waitcnt vmcnt(0)
	ds_write_b128 v171, v[40:43]
	s_waitcnt lgkmcnt(0)
	s_nop 2
	v_cvt_pk_bf16_f32 v110, v124, v125
	v_cvt_pk_bf16_f32 v111, v126, v127
	global_store_dwordx2 v[250:251], v[110:111], off
	v_add_co_u32_e32 v112, vcc, 0x20000, v250
	v_cvt_pk_bf16_f32 v114, v120, v121
	v_cvt_pk_bf16_f32 v115, v122, v123
	v_addc_co_u32_e32 v113, vcc, 0, v251, vcc
	global_store_dwordx2 v[112:113], v[114:115], off
	v_add_co_u32_e32 v124, vcc, 0x40000, v250
	v_cvt_pk_bf16_f32 v126, v116, v117
	v_cvt_pk_bf16_f32 v127, v118, v119
	v_addc_co_u32_e32 v125, vcc, 0, v251, vcc
	global_store_dwordx2 v[124:125], v[126:127], off
	v_add_co_u32_e32 v120, vcc, 0x60000, v250
	v_cvt_pk_bf16_f32 v122, v104, v105
	v_cvt_pk_bf16_f32 v123, v106, v107
	v_addc_co_u32_e32 v121, vcc, 0, v251, vcc
	global_store_dwordx2 v[120:121], v[122:123], off
	s_cmp_eq_u32 s40, 32
	s_cbranch_scc1 .LBB0_334
.LBB0_341:
.Lret_bar1:
	s_barrier
	s_add_i32 s42, s40, 5
	s_add_i32 s43, s40, 1
	s_min_i32 s43, s43, 31
	s_cmp_lt_u32 s13, 3
	s_cselect_b32 s13, s42, s43
	s_cselect_b32 s42, 3, 31
	s_cselect_b32 s67, s33, s1
	s_sub_i32 vcc_lo, s42, s13
	s_and_b64 s[42:43], exec, s[74:75]
	s_cselect_b32 s13, s13, vcc_lo
	s_lshl_b32 s47, s13, 6
	s_add_i32 s47, s47, s67
